# combo: v_g2 + attention wave-role permutation + RNN conv/gate LDS->MFMA chains pipelined
# speedup vs baseline: 1.0001x; 1.0001x over previous
.LBB0_936:
	v_ashrrev_i32_e32 v75, 31, v74
	v_lshl_add_u64 v[84:85], s[82:83], 0, v[74:75]
	v_mad_u64_u32 v[0:1], s[58:59], v84, s94, v[70:71]
	v_mad_i32_i24 v1, v85, s94, v1
	global_load_dwordx2 v[82:83], v[0:1], off
	global_load_dwordx2 v[80:81], v[0:1], off offset:16
	global_load_dwordx2 v[78:79], v[0:1], off offset:32
	global_load_dwordx2 v[76:77], v[0:1], off offset:48
	ds_read_b128 v[0:3], v99 offset:16384
	ds_read_b128 v[20:23], v99 offset:17408
	s_and_b32 s84, s84, 1
	v_mov_b64_e32 v[16:17], s[52:53]
	s_mul_i32 s1, s84, 0x8400
	v_mov_b64_e32 v[18:19], s[54:55]
	s_add_i32 s85, s1, 0x100
	v_add_u32_e32 v40, s85, v136
	s_lshl_b32 s1, s84, 11
	s_add_i32 vcc_lo, s1, 0x100
	v_add_u32_e32 v234, v40, v104
	ds_read_b128 v[186:189], v234 offset:16384
	ds_read_b128 v[190:193], v99
	v_add_u32_e32 v234, v40, v106
	ds_read_b128 v[194:197], v234 offset:16384
	ds_read_b128 v[198:201], v99 offset:1024
	v_add_u32_e32 v234, v40, v107
	ds_read_b128 v[202:205], v234 offset:16384
	ds_read_b128 v[206:209], v99 offset:8192
	v_add_u32_e32 v234, v40, v109
	ds_read_b128 v[210:213], v234 offset:16384
	ds_read_b128 v[214:217], v99 offset:9216
	v_add_u32_e32 v40, s85, v133
	v_add_u32_e32 v234, v40, v135
	ds_read_b128 v[218:221], v234 offset:16384
	ds_read_b128 v[222:225], v99 offset:2048
	v_add_u32_e32 v234, v40, v134
	ds_read_b128 v[226:229], v234 offset:16384
	ds_read_b128 v[230:233], v99 offset:3072
	s_waitcnt lgkmcnt(13)
	v_mfma_f32_32x32x16_bf16 v[0:15], v[0:3], v[16:19], 0
	s_waitcnt lgkmcnt(12)
	v_mfma_f32_32x32x16_bf16 v[16:31], v[20:23], v[16:19], 0
	s_waitcnt lgkmcnt(10)
	v_mfma_f32_32x32x16_bf16 v[0:15], v[190:193], v[186:189], v[0:15]
	v_add_u32_e32 v234, v40, v132
	ds_read_b128 v[186:189], v234 offset:16384
	ds_read_b128 v[190:193], v99 offset:10240
	s_waitcnt lgkmcnt(10)
	v_mfma_f32_32x32x16_bf16 v[0:15], v[198:201], v[194:197], v[0:15]
	v_add_u32_e32 v234, v40, v131
	ds_read_b128 v[194:197], v234 offset:16384
	ds_read_b128 v[198:201], v99 offset:11264
	s_waitcnt lgkmcnt(10)
	v_mfma_f32_32x32x16_bf16 v[16:31], v[206:209], v[202:205], v[16:31]
	v_add_u32_e32 v40, s85, v129
	v_add_u32_e32 v234, v40, v130
	ds_read_b128 v[202:205], v234 offset:16384
	ds_read_b128 v[206:209], v99 offset:4096
	s_waitcnt lgkmcnt(10)
	v_mfma_f32_32x32x16_bf16 v[16:31], v[214:217], v[210:213], v[16:31]
	v_add_u32_e32 v234, v40, v128
	ds_read_b128 v[210:213], v234 offset:16384
	ds_read_b128 v[214:217], v99 offset:5120
	s_waitcnt lgkmcnt(10)
	v_mfma_f32_32x32x16_bf16 v[0:15], v[222:225], v[218:221], v[0:15]
	v_add_u32_e32 v234, v40, v127
	ds_read_b128 v[218:221], v234 offset:16384
	ds_read_b128 v[222:225], v99 offset:12288
	s_waitcnt lgkmcnt(10)
	v_mfma_f32_32x32x16_bf16 v[0:15], v[230:233], v[226:229], v[0:15]
	v_add_u32_e32 v234, v40, v126
	ds_read_b128 v[226:229], v234 offset:16384
	ds_read_b128 v[230:233], v99 offset:13312
	s_waitcnt lgkmcnt(10)
	v_mfma_f32_32x32x16_bf16 v[16:31], v[190:193], v[186:189], v[16:31]
	v_add_u32_e32 v40, s85, v124
	v_add_u32_e32 v234, v40, v125
	ds_read_b128 v[186:189], v234 offset:16384
	ds_read_b128 v[190:193], v99 offset:6144
	s_waitcnt lgkmcnt(10)
	v_mfma_f32_32x32x16_bf16 v[16:31], v[198:201], v[194:197], v[16:31]
	v_add_u32_e32 v234, v40, v123
	ds_read_b128 v[194:197], v234 offset:16384
	ds_read_b128 v[198:201], v99 offset:7168
	s_waitcnt lgkmcnt(10)
	v_mfma_f32_32x32x16_bf16 v[0:15], v[206:209], v[202:205], v[0:15]
	v_add_u32_e32 v234, v40, v122
	ds_read_b128 v[202:205], v234 offset:16384
	ds_read_b128 v[206:209], v99 offset:14336
	s_waitcnt lgkmcnt(10)
	v_mfma_f32_32x32x16_bf16 v[0:15], v[214:217], v[210:213], v[0:15]
	v_add_u32_e32 v234, v40, v121
	ds_read_b128 v[210:213], v234 offset:16384
	ds_read_b128 v[214:217], v99 offset:15360
	s_waitcnt lgkmcnt(10)
	v_mfma_f32_32x32x16_bf16 v[16:31], v[222:225], v[218:221], v[16:31]
	s_waitcnt lgkmcnt(8)
	v_mfma_f32_32x32x16_bf16 v[16:31], v[230:233], v[226:229], v[16:31]
	s_waitcnt lgkmcnt(6)
	v_mfma_f32_32x32x16_bf16 v[0:15], v[190:193], v[186:189], v[0:15]
	s_waitcnt lgkmcnt(4)
	v_mfma_f32_32x32x16_bf16 v[0:15], v[198:201], v[194:197], v[0:15]
	s_waitcnt lgkmcnt(2)
	v_mfma_f32_32x32x16_bf16 v[16:31], v[206:209], v[202:205], v[16:31]
	s_waitcnt lgkmcnt(0)
	v_mfma_f32_32x32x16_bf16 v[16:31], v[214:217], v[210:213], v[16:31]
	s_nop 9
	v_cvt_pk_bf16_f32 v60, v0, v1
	v_cvt_pk_bf16_f32 v61, v2, v3
	v_cvt_pk_bf16_f32 v62, v4, v5
	v_cvt_pk_bf16_f32 v63, v6, v7
	v_cvt_pk_bf16_f32 v56, v8, v9
	v_cvt_pk_bf16_f32 v57, v10, v11
	v_cvt_pk_bf16_f32 v58, v12, v13
	v_cvt_pk_bf16_f32 v59, v14, v15
	v_cvt_pk_bf16_f32 v52, v16, v17
	v_cvt_pk_bf16_f32 v53, v18, v19
	v_cvt_pk_bf16_f32 v54, v20, v21
	v_cvt_pk_bf16_f32 v55, v22, v23
	v_cvt_pk_bf16_f32 v48, v24, v25
	v_cvt_pk_bf16_f32 v49, v26, v27
	v_cvt_pk_bf16_f32 v50, v28, v29
	v_cvt_pk_bf16_f32 v51, v30, v31
	v_cndmask_b32_e64 v149, v16, v0, s[30:31]
	v_cndmask_b32_e64 v148, v17, v1, s[30:31]
	v_cndmask_b32_e64 v147, v18, v2, s[30:31]
	v_cndmask_b32_e64 v146, v19, v3, s[30:31]
	v_cndmask_b32_e64 v145, v20, v4, s[30:31]
	v_cndmask_b32_e64 v144, v21, v5, s[30:31]
	v_cndmask_b32_e64 v143, v22, v6, s[30:31]
	v_cndmask_b32_e64 v142, v23, v7, s[30:31]
	v_cndmask_b32_e64 v141, v24, v8, s[30:31]
	v_cndmask_b32_e64 v140, v25, v9, s[30:31]
	v_cndmask_b32_e64 v139, v26, v10, s[30:31]
	v_cndmask_b32_e64 v138, v27, v11, s[30:31]
	v_cndmask_b32_e64 v137, v28, v12, s[30:31]
	v_cndmask_b32_e64 v87, v29, v13, s[30:31]
	v_cndmask_b32_e64 v86, v30, v14, s[30:31]
	v_cndmask_b32_e64 v75, v31, v15, s[30:31]
	ds_read_b128 v[16:19], v102 offset:1536
	ds_read_b128 v[20:23], v102 offset:1568
	ds_read_b128 v[0:3], v102 offset:1664
	ds_read_b128 v[44:47], v102 offset:1792
	ds_read_b128 v[4:7], v102 offset:1696
	ds_read_b128 v[40:43], v102 offset:1824
	ds_read_b128 v[24:27], v102 offset:1600
	ds_read_b128 v[8:11], v102 offset:1728
	ds_read_b128 v[36:39], v102 offset:1856
	ds_read_b128 v[28:31], v102 offset:1632
	ds_read_b128 v[12:15], v102 offset:1760
	ds_read_b128 v[32:35], v102 offset:1888
	ds_read_b128 v[186:189], v98 offset:8192
	ds_read_b128 v[190:193], v98 offset:12288
	ds_read_b128 v[194:197], v98 offset:9216
	ds_read_b128 v[198:201], v98 offset:13312
	ds_read_b128 v[202:205], v98 offset:10240
	ds_read_b128 v[206:209], v98 offset:14336
	ds_read_b128 v[210:213], v98 offset:11264
	ds_read_b128 v[214:217], v98 offset:15360
	s_waitcnt lgkmcnt(7)
	v_mfma_f32_32x32x16_bf16 v[16:31], v[186:189], v[60:63], v[16:31]
	s_waitcnt lgkmcnt(6)
	v_mfma_f32_32x32x16_bf16 v[0:15], v[190:193], v[60:63], v[0:15]
	s_waitcnt lgkmcnt(5)
	v_mfma_f32_32x32x16_bf16 v[16:31], v[194:197], v[56:59], v[16:31]
	s_waitcnt lgkmcnt(4)
	v_mfma_f32_32x32x16_bf16 v[0:15], v[198:201], v[56:59], v[0:15]
	s_waitcnt lgkmcnt(3)
	v_mfma_f32_32x32x16_bf16 v[16:31], v[202:205], v[52:55], v[16:31]
	s_waitcnt lgkmcnt(2)
	v_mfma_f32_32x32x16_bf16 v[0:15], v[206:209], v[52:55], v[0:15]
	s_waitcnt lgkmcnt(1)
	v_mfma_f32_32x32x16_bf16 v[16:31], v[210:213], v[48:51], v[16:31]
	s_waitcnt lgkmcnt(0)
	v_mfma_f32_32x32x16_bf16 v[0:15], v[214:217], v[48:51], v[0:15]
	s_nop 8
	v_exp_f32_e32 v16, v16
	v_exp_f32_e32 v17, v17
	v_exp_f32_e32 v18, v18
	v_exp_f32_e32 v19, v19
	v_add_f32_e32 v16, 1.0, v16
	v_add_f32_e32 v17, 1.0, v17
	v_rcp_f32_e32 v16, v16
	v_exp_f32_e32 v0, v0
	v_exp_f32_e32 v1, v1
	v_rcp_f32_e32 v17, v17
	v_add_f32_e32 v18, 1.0, v18
	v_add_f32_e32 v0, 1.0, v0
	v_add_f32_e32 v1, 1.0, v1
	v_rcp_f32_e32 v48, v0
	v_mul_f32_e32 v0, v44, v16
	v_rcp_f32_e32 v44, v1
	v_mul_f32_e32 v1, v45, v17
	v_exp_f32_e32 v1, v1
	v_exp_f32_e32 v2, v2
	v_rcp_f32_e32 v18, v18
	v_add_f32_e32 v19, 1.0, v19
	v_fma_f32 v17, -v1, v1, 1.0
	v_max_f32_e32 v17, 0, v17
	v_sqrt_f32_e32 v17, v17
	v_add_f32_e32 v2, 1.0, v2
	v_exp_f32_e32 v3, v3
	v_rcp_f32_e32 v19, v19
	v_mul_f32_e32 v17, v44, v17
	v_rcp_f32_e32 v44, v2
	v_mul_f32_e32 v2, v46, v18
	v_exp_f32_e32 v2, v2
	v_add_f32_e32 v3, 1.0, v3
	v_exp_f32_e32 v20, v20
	v_exp_f32_e32 v21, v21
	v_fma_f32 v18, -v2, v2, 1.0
	v_max_f32_e32 v18, 0, v18
	v_sqrt_f32_e32 v18, v18
	v_add_f32_e32 v20, 1.0, v20
	v_exp_f32_e32 v4, v4
	v_add_f32_e32 v21, 1.0, v21
	v_mul_f32_e32 v18, v44, v18
	v_rcp_f32_e32 v44, v3
	v_mul_f32_e32 v3, v47, v19
	v_exp_f32_e32 v3, v3
	v_exp_f32_e32 v5, v5
	v_rcp_f32_e32 v20, v20
	v_rcp_f32_e32 v21, v21
	v_fma_f32 v19, -v3, v3, 1.0
	v_max_f32_e32 v19, 0, v19
	v_sqrt_f32_e32 v19, v19
	v_add_f32_e32 v4, 1.0, v4
	v_add_f32_e32 v5, 1.0, v5
	v_exp_f32_e32 v22, v22
	v_mul_f32_e32 v19, v44, v19
	v_rcp_f32_e32 v44, v4
	v_mul_f32_e32 v4, v40, v20
	v_rcp_f32_e32 v40, v5
	v_mul_f32_e32 v5, v41, v21
	v_exp_f32_e32 v5, v5
	v_add_f32_e32 v22, 1.0, v22
	v_exp_f32_e32 v6, v6
	v_rcp_f32_e32 v22, v22
	v_fma_f32 v21, -v5, v5, 1.0
	v_max_f32_e32 v21, 0, v21
	v_sqrt_f32_e32 v21, v21
	v_add_f32_e32 v6, 1.0, v6
	v_exp_f32_e32 v23, v23
	v_exp_f32_e32 v7, v7
	v_mul_f32_e32 v21, v40, v21
	v_rcp_f32_e32 v40, v6
	v_mul_f32_e32 v6, v42, v22
	v_exp_f32_e32 v6, v6
	v_add_f32_e32 v23, 1.0, v23
	v_rcp_f32_e32 v23, v23
	v_add_f32_e32 v7, 1.0, v7
	v_fma_f32 v22, -v6, v6, 1.0
	v_max_f32_e32 v22, 0, v22
	v_sqrt_f32_e32 v22, v22
	v_exp_f32_e32 v24, v24
	v_exp_f32_e32 v25, v25
	v_exp_f32_e32 v8, v8
	v_mul_f32_e32 v22, v40, v22
	v_rcp_f32_e32 v40, v7
	v_mul_f32_e32 v7, v43, v23
	v_exp_f32_e32 v7, v7
	v_add_f32_e32 v24, 1.0, v24
	v_add_f32_e32 v25, 1.0, v25
	v_exp_f32_e32 v9, v9
	v_fma_f32 v23, -v7, v7, 1.0
	v_max_f32_e32 v23, 0, v23
	v_sqrt_f32_e32 v23, v23
	v_rcp_f32_e32 v24, v24
	v_rcp_f32_e32 v25, v25
	v_add_f32_e32 v8, 1.0, v8
	v_add_f32_e32 v9, 1.0, v9
	v_mul_f32_e32 v23, v40, v23
	v_rcp_f32_e32 v40, v8
	v_mul_f32_e32 v8, v36, v24
	v_rcp_f32_e32 v36, v9
	v_mul_f32_e32 v9, v37, v25
	v_exp_f32_e32 v9, v9
	v_exp_f32_e32 v26, v26
	v_exp_f32_e32 v10, v10
	v_exp_f32_e32 v27, v27
	v_fma_f32 v25, -v9, v9, 1.0
	v_max_f32_e32 v25, 0, v25
	v_add_f32_e32 v26, 1.0, v26
	v_sqrt_f32_e32 v25, v25
	v_rcp_f32_e32 v26, v26
	v_add_f32_e32 v10, 1.0, v10
	v_add_f32_e32 v27, 1.0, v27
	v_mul_f32_e32 v25, v36, v25
	v_rcp_f32_e32 v36, v10
	v_mul_f32_e32 v10, v38, v26
	v_exp_f32_e32 v10, v10
	v_exp_f32_e32 v11, v11
	v_rcp_f32_e32 v27, v27
	v_exp_f32_e32 v28, v28
	v_fma_f32 v26, -v10, v10, 1.0
	v_max_f32_e32 v26, 0, v26
	v_sqrt_f32_e32 v26, v26
	v_add_f32_e32 v11, 1.0, v11
	v_exp_f32_e32 v29, v29
	v_add_f32_e32 v28, 1.0, v28
	v_mul_f32_e32 v26, v36, v26
	v_rcp_f32_e32 v36, v11
	v_mul_f32_e32 v11, v39, v27
	v_exp_f32_e32 v11, v11
	v_exp_f32_e32 v12, v12
	v_add_f32_e32 v29, 1.0, v29
	v_exp_f32_e32 v13, v13
	v_fma_f32 v27, -v11, v11, 1.0
	v_max_f32_e32 v27, 0, v27
	v_sqrt_f32_e32 v27, v27
	v_rcp_f32_e32 v28, v28
	v_rcp_f32_e32 v29, v29
	v_add_f32_e32 v12, 1.0, v12
	v_add_f32_e32 v13, 1.0, v13
	v_mul_f32_e32 v27, v36, v27
	v_rcp_f32_e32 v36, v12
	v_mul_f32_e32 v12, v32, v28
	v_rcp_f32_e32 v32, v13
	v_mul_f32_e32 v13, v33, v29
	v_exp_f32_e32 v13, v13
	v_exp_f32_e32 v30, v30
	v_exp_f32_e32 v14, v14
	v_exp_f32_e32 v31, v31
	v_fma_f32 v29, -v13, v13, 1.0
	v_max_f32_e32 v29, 0, v29
	v_add_f32_e32 v30, 1.0, v30
	v_sqrt_f32_e32 v29, v29
	v_rcp_f32_e32 v30, v30
	v_add_f32_e32 v14, 1.0, v14
	v_add_f32_e32 v31, 1.0, v31
	v_mul_f32_e32 v29, v32, v29
	v_rcp_f32_e32 v32, v14
	v_mul_f32_e32 v14, v34, v30
	v_exp_f32_e32 v14, v14
	v_exp_f32_e32 v15, v15
	v_rcp_f32_e32 v31, v31
	v_exp_f32_e32 v0, v0
	v_fma_f32 v30, -v14, v14, 1.0
	v_max_f32_e32 v30, 0, v30
	v_sqrt_f32_e32 v30, v30
	v_add_f32_e32 v15, 1.0, v15
	v_exp_f32_e32 v4, v4
	v_exp_f32_e32 v8, v8
	v_mul_f32_e32 v30, v32, v30
	v_rcp_f32_e32 v32, v15
	v_mul_f32_e32 v15, v35, v31
	v_exp_f32_e32 v12, v12
	v_exp_f32_e32 v15, v15
	v_fma_f32 v16, -v0, v0, 1.0
	v_fma_f32 v20, -v4, v4, 1.0
	v_fma_f32 v24, -v8, v8, 1.0
	v_fma_f32 v28, -v12, v12, 1.0
	v_fma_f32 v31, -v15, v15, 1.0
	v_max_f32_e32 v16, 0, v16
	v_max_f32_e32 v20, 0, v20
	v_max_f32_e32 v24, 0, v24
	v_max_f32_e32 v28, 0, v28
	v_max_f32_e32 v31, 0, v31
	v_sqrt_f32_e32 v16, v16
	v_sqrt_f32_e32 v20, v20
	v_sqrt_f32_e32 v24, v24
	v_sqrt_f32_e32 v28, v28
	v_sqrt_f32_e32 v31, v31
	v_mul_f32_e32 v16, v48, v16
	v_mul_f32_e32 v20, v44, v20
	v_mul_f32_e32 v24, v40, v24
	v_mul_f32_e32 v28, v36, v28
	v_mul_f32_e32 v31, v32, v31
	v_mul_f32_e32 v16, v149, v16
	v_mul_f32_e32 v17, v148, v17
	v_mul_f32_e32 v18, v147, v18
	v_mul_f32_e32 v19, v146, v19
	v_mul_f32_e32 v20, v145, v20
	v_mul_f32_e32 v21, v144, v21
	v_mul_f32_e32 v22, v143, v22
	v_mul_f32_e32 v23, v142, v23
	v_mul_f32_e32 v24, v141, v24
	v_mul_f32_e32 v25, v140, v25
	v_mul_f32_e32 v26, v139, v26
	v_mul_f32_e32 v27, v138, v27
	v_mul_f32_e32 v28, v137, v28
	v_mul_f32_e32 v29, v87, v29
	v_mul_f32_e32 v30, v86, v30
	v_mul_f32_e32 v31, v75, v31
	s_nop 1
	v_fmac_f32_dpp v16, v16, v0 row_shr:1 row_mask:0xf bank_mask:0xf
	v_fmac_f32_dpp v17, v17, v1 row_shr:1 row_mask:0xf bank_mask:0xf
	v_fmac_f32_dpp v18, v18, v2 row_shr:1 row_mask:0xf bank_mask:0xf
	v_fmac_f32_dpp v19, v19, v3 row_shr:1 row_mask:0xf bank_mask:0xf
	v_fmac_f32_dpp v20, v20, v4 row_shr:1 row_mask:0xf bank_mask:0xf
	v_fmac_f32_dpp v21, v21, v5 row_shr:1 row_mask:0xf bank_mask:0xf
	v_fmac_f32_dpp v22, v22, v6 row_shr:1 row_mask:0xf bank_mask:0xf
	v_fmac_f32_dpp v23, v23, v7 row_shr:1 row_mask:0xf bank_mask:0xf
	v_mul_f32_dpp v0, v0, v0 row_shr:1 row_mask:0xf bank_mask:0xf
	v_mul_f32_dpp v1, v1, v1 row_shr:1 row_mask:0xf bank_mask:0xf
	v_mul_f32_dpp v2, v2, v2 row_shr:1 row_mask:0xf bank_mask:0xf
	v_mul_f32_dpp v3, v3, v3 row_shr:1 row_mask:0xf bank_mask:0xf
	v_mul_f32_dpp v4, v4, v4 row_shr:1 row_mask:0xf bank_mask:0xf
	v_mul_f32_dpp v5, v5, v5 row_shr:1 row_mask:0xf bank_mask:0xf
	v_mul_f32_dpp v6, v6, v6 row_shr:1 row_mask:0xf bank_mask:0xf
	v_mul_f32_dpp v7, v7, v7 row_shr:1 row_mask:0xf bank_mask:0xf
	v_fmac_f32_dpp v16, v16, v0 row_shr:2 row_mask:0xf bank_mask:0xf
	v_fmac_f32_dpp v17, v17, v1 row_shr:2 row_mask:0xf bank_mask:0xf
	v_fmac_f32_dpp v18, v18, v2 row_shr:2 row_mask:0xf bank_mask:0xf
	v_fmac_f32_dpp v19, v19, v3 row_shr:2 row_mask:0xf bank_mask:0xf
	v_fmac_f32_dpp v20, v20, v4 row_shr:2 row_mask:0xf bank_mask:0xf
	v_fmac_f32_dpp v21, v21, v5 row_shr:2 row_mask:0xf bank_mask:0xf
	v_fmac_f32_dpp v22, v22, v6 row_shr:2 row_mask:0xf bank_mask:0xf
	v_fmac_f32_dpp v23, v23, v7 row_shr:2 row_mask:0xf bank_mask:0xf
	v_mul_f32_dpp v0, v0, v0 row_shr:2 row_mask:0xf bank_mask:0xf
	v_mul_f32_dpp v1, v1, v1 row_shr:2 row_mask:0xf bank_mask:0xf
	v_mul_f32_dpp v2, v2, v2 row_shr:2 row_mask:0xf bank_mask:0xf
	v_mul_f32_dpp v3, v3, v3 row_shr:2 row_mask:0xf bank_mask:0xf
	v_mul_f32_dpp v4, v4, v4 row_shr:2 row_mask:0xf bank_mask:0xf
	v_mul_f32_dpp v5, v5, v5 row_shr:2 row_mask:0xf bank_mask:0xf
	v_mul_f32_dpp v6, v6, v6 row_shr:2 row_mask:0xf bank_mask:0xf
	v_mul_f32_dpp v7, v7, v7 row_shr:2 row_mask:0xf bank_mask:0xf
	v_fmac_f32_dpp v16, v16, v0 row_shr:4 row_mask:0xf bank_mask:0xf
	v_fmac_f32_dpp v17, v17, v1 row_shr:4 row_mask:0xf bank_mask:0xf
	v_fmac_f32_dpp v18, v18, v2 row_shr:4 row_mask:0xf bank_mask:0xf
	v_fmac_f32_dpp v19, v19, v3 row_shr:4 row_mask:0xf bank_mask:0xf
	v_fmac_f32_dpp v20, v20, v4 row_shr:4 row_mask:0xf bank_mask:0xf
	v_fmac_f32_dpp v21, v21, v5 row_shr:4 row_mask:0xf bank_mask:0xf
	v_fmac_f32_dpp v22, v22, v6 row_shr:4 row_mask:0xf bank_mask:0xf
	v_fmac_f32_dpp v23, v23, v7 row_shr:4 row_mask:0xf bank_mask:0xf
	v_mul_f32_dpp v0, v0, v0 row_shr:4 row_mask:0xf bank_mask:0xf
	v_mul_f32_dpp v1, v1, v1 row_shr:4 row_mask:0xf bank_mask:0xf
	v_mul_f32_dpp v2, v2, v2 row_shr:4 row_mask:0xf bank_mask:0xf
	v_mul_f32_dpp v3, v3, v3 row_shr:4 row_mask:0xf bank_mask:0xf
	v_mul_f32_dpp v4, v4, v4 row_shr:4 row_mask:0xf bank_mask:0xf
	v_mul_f32_dpp v5, v5, v5 row_shr:4 row_mask:0xf bank_mask:0xf
	v_mul_f32_dpp v6, v6, v6 row_shr:4 row_mask:0xf bank_mask:0xf
	v_mul_f32_dpp v7, v7, v7 row_shr:4 row_mask:0xf bank_mask:0xf
	v_fmac_f32_dpp v16, v16, v0 row_shr:8 row_mask:0xf bank_mask:0xf
	v_fmac_f32_dpp v17, v17, v1 row_shr:8 row_mask:0xf bank_mask:0xf
	v_fmac_f32_dpp v18, v18, v2 row_shr:8 row_mask:0xf bank_mask:0xf
	v_fmac_f32_dpp v19, v19, v3 row_shr:8 row_mask:0xf bank_mask:0xf
	v_fmac_f32_dpp v20, v20, v4 row_shr:8 row_mask:0xf bank_mask:0xf
	v_fmac_f32_dpp v21, v21, v5 row_shr:8 row_mask:0xf bank_mask:0xf
	v_fmac_f32_dpp v22, v22, v6 row_shr:8 row_mask:0xf bank_mask:0xf
	v_fmac_f32_dpp v23, v23, v7 row_shr:8 row_mask:0xf bank_mask:0xf
	v_mul_f32_dpp v0, v0, v0 row_shr:8 row_mask:0xf bank_mask:0xf
	v_mul_f32_dpp v1, v1, v1 row_shr:8 row_mask:0xf bank_mask:0xf
	v_mul_f32_dpp v2, v2, v2 row_shr:8 row_mask:0xf bank_mask:0xf
	v_mul_f32_dpp v3, v3, v3 row_shr:8 row_mask:0xf bank_mask:0xf
	v_mul_f32_dpp v4, v4, v4 row_shr:8 row_mask:0xf bank_mask:0xf
	v_mul_f32_dpp v5, v5, v5 row_shr:8 row_mask:0xf bank_mask:0xf
	v_mul_f32_dpp v6, v6, v6 row_shr:8 row_mask:0xf bank_mask:0xf
	v_mul_f32_dpp v7, v7, v7 row_shr:8 row_mask:0xf bank_mask:0xf
	v_fmac_f32_dpp v16, v16, v0 row_bcast:15 row_mask:0xa bank_mask:0xf
	v_fmac_f32_dpp v17, v17, v1 row_bcast:15 row_mask:0xa bank_mask:0xf
	v_fmac_f32_dpp v18, v18, v2 row_bcast:15 row_mask:0xa bank_mask:0xf
	v_fmac_f32_dpp v19, v19, v3 row_bcast:15 row_mask:0xa bank_mask:0xf
	v_fmac_f32_dpp v20, v20, v4 row_bcast:15 row_mask:0xa bank_mask:0xf
	v_fmac_f32_dpp v21, v21, v5 row_bcast:15 row_mask:0xa bank_mask:0xf
	v_fmac_f32_dpp v22, v22, v6 row_bcast:15 row_mask:0xa bank_mask:0xf
	v_fmac_f32_dpp v23, v23, v7 row_bcast:15 row_mask:0xa bank_mask:0xf
	v_mul_f32_dpp v0, v0, v0 row_bcast:15 row_mask:0xa bank_mask:0xf
	v_mul_f32_dpp v1, v1, v1 row_bcast:15 row_mask:0xa bank_mask:0xf
	v_mul_f32_dpp v2, v2, v2 row_bcast:15 row_mask:0xa bank_mask:0xf
	v_mul_f32_dpp v3, v3, v3 row_bcast:15 row_mask:0xa bank_mask:0xf
	v_mul_f32_dpp v4, v4, v4 row_bcast:15 row_mask:0xa bank_mask:0xf
	v_mul_f32_dpp v5, v5, v5 row_bcast:15 row_mask:0xa bank_mask:0xf
	v_mul_f32_dpp v6, v6, v6 row_bcast:15 row_mask:0xa bank_mask:0xf
	v_mul_f32_dpp v7, v7, v7 row_bcast:15 row_mask:0xa bank_mask:0xf

	s_nop 1
	v_fmac_f32_dpp v24, v24, v8 row_shr:1 row_mask:0xf bank_mask:0xf
	v_fmac_f32_dpp v25, v25, v9 row_shr:1 row_mask:0xf bank_mask:0xf
	v_fmac_f32_dpp v26, v26, v10 row_shr:1 row_mask:0xf bank_mask:0xf
	v_fmac_f32_dpp v27, v27, v11 row_shr:1 row_mask:0xf bank_mask:0xf
	v_fmac_f32_dpp v28, v28, v12 row_shr:1 row_mask:0xf bank_mask:0xf
	v_fmac_f32_dpp v29, v29, v13 row_shr:1 row_mask:0xf bank_mask:0xf
	v_fmac_f32_dpp v30, v30, v14 row_shr:1 row_mask:0xf bank_mask:0xf
	v_fmac_f32_dpp v31, v31, v15 row_shr:1 row_mask:0xf bank_mask:0xf
	v_mul_f32_dpp v8, v8, v8 row_shr:1 row_mask:0xf bank_mask:0xf
	v_mul_f32_dpp v9, v9, v9 row_shr:1 row_mask:0xf bank_mask:0xf
	v_mul_f32_dpp v10, v10, v10 row_shr:1 row_mask:0xf bank_mask:0xf
	v_mul_f32_dpp v11, v11, v11 row_shr:1 row_mask:0xf bank_mask:0xf
	v_mul_f32_dpp v12, v12, v12 row_shr:1 row_mask:0xf bank_mask:0xf
	v_mul_f32_dpp v13, v13, v13 row_shr:1 row_mask:0xf bank_mask:0xf
	v_mul_f32_dpp v14, v14, v14 row_shr:1 row_mask:0xf bank_mask:0xf
	v_mul_f32_dpp v15, v15, v15 row_shr:1 row_mask:0xf bank_mask:0xf
	v_fmac_f32_dpp v24, v24, v8 row_shr:2 row_mask:0xf bank_mask:0xf
	v_fmac_f32_dpp v25, v25, v9 row_shr:2 row_mask:0xf bank_mask:0xf
	v_fmac_f32_dpp v26, v26, v10 row_shr:2 row_mask:0xf bank_mask:0xf
	v_fmac_f32_dpp v27, v27, v11 row_shr:2 row_mask:0xf bank_mask:0xf
	v_fmac_f32_dpp v28, v28, v12 row_shr:2 row_mask:0xf bank_mask:0xf
	v_fmac_f32_dpp v29, v29, v13 row_shr:2 row_mask:0xf bank_mask:0xf
	v_fmac_f32_dpp v30, v30, v14 row_shr:2 row_mask:0xf bank_mask:0xf
	v_fmac_f32_dpp v31, v31, v15 row_shr:2 row_mask:0xf bank_mask:0xf
	v_mul_f32_dpp v8, v8, v8 row_shr:2 row_mask:0xf bank_mask:0xf
	v_mul_f32_dpp v9, v9, v9 row_shr:2 row_mask:0xf bank_mask:0xf
	v_mul_f32_dpp v10, v10, v10 row_shr:2 row_mask:0xf bank_mask:0xf
	v_mul_f32_dpp v11, v11, v11 row_shr:2 row_mask:0xf bank_mask:0xf
	v_mul_f32_dpp v12, v12, v12 row_shr:2 row_mask:0xf bank_mask:0xf
	v_mul_f32_dpp v13, v13, v13 row_shr:2 row_mask:0xf bank_mask:0xf
	v_mul_f32_dpp v14, v14, v14 row_shr:2 row_mask:0xf bank_mask:0xf
	v_mul_f32_dpp v15, v15, v15 row_shr:2 row_mask:0xf bank_mask:0xf
	v_fmac_f32_dpp v24, v24, v8 row_shr:4 row_mask:0xf bank_mask:0xf
	v_fmac_f32_dpp v25, v25, v9 row_shr:4 row_mask:0xf bank_mask:0xf
	v_fmac_f32_dpp v26, v26, v10 row_shr:4 row_mask:0xf bank_mask:0xf
	v_fmac_f32_dpp v27, v27, v11 row_shr:4 row_mask:0xf bank_mask:0xf
	v_fmac_f32_dpp v28, v28, v12 row_shr:4 row_mask:0xf bank_mask:0xf
	v_fmac_f32_dpp v29, v29, v13 row_shr:4 row_mask:0xf bank_mask:0xf
	v_fmac_f32_dpp v30, v30, v14 row_shr:4 row_mask:0xf bank_mask:0xf
	v_fmac_f32_dpp v31, v31, v15 row_shr:4 row_mask:0xf bank_mask:0xf
	v_mul_f32_dpp v8, v8, v8 row_shr:4 row_mask:0xf bank_mask:0xf
	v_mul_f32_dpp v9, v9, v9 row_shr:4 row_mask:0xf bank_mask:0xf
	v_mul_f32_dpp v10, v10, v10 row_shr:4 row_mask:0xf bank_mask:0xf
	v_mul_f32_dpp v11, v11, v11 row_shr:4 row_mask:0xf bank_mask:0xf
	v_mul_f32_dpp v12, v12, v12 row_shr:4 row_mask:0xf bank_mask:0xf
	v_mul_f32_dpp v13, v13, v13 row_shr:4 row_mask:0xf bank_mask:0xf
	v_mul_f32_dpp v14, v14, v14 row_shr:4 row_mask:0xf bank_mask:0xf
	v_mul_f32_dpp v15, v15, v15 row_shr:4 row_mask:0xf bank_mask:0xf
	v_fmac_f32_dpp v24, v24, v8 row_shr:8 row_mask:0xf bank_mask:0xf
	v_fmac_f32_dpp v25, v25, v9 row_shr:8 row_mask:0xf bank_mask:0xf
	v_fmac_f32_dpp v26, v26, v10 row_shr:8 row_mask:0xf bank_mask:0xf
	v_fmac_f32_dpp v27, v27, v11 row_shr:8 row_mask:0xf bank_mask:0xf
	v_fmac_f32_dpp v28, v28, v12 row_shr:8 row_mask:0xf bank_mask:0xf
	v_fmac_f32_dpp v29, v29, v13 row_shr:8 row_mask:0xf bank_mask:0xf
	v_fmac_f32_dpp v30, v30, v14 row_shr:8 row_mask:0xf bank_mask:0xf
	v_fmac_f32_dpp v31, v31, v15 row_shr:8 row_mask:0xf bank_mask:0xf
	v_mul_f32_dpp v8, v8, v8 row_shr:8 row_mask:0xf bank_mask:0xf
	v_mul_f32_dpp v9, v9, v9 row_shr:8 row_mask:0xf bank_mask:0xf
	v_mul_f32_dpp v10, v10, v10 row_shr:8 row_mask:0xf bank_mask:0xf
	v_mul_f32_dpp v11, v11, v11 row_shr:8 row_mask:0xf bank_mask:0xf
	v_mul_f32_dpp v12, v12, v12 row_shr:8 row_mask:0xf bank_mask:0xf
	v_mul_f32_dpp v13, v13, v13 row_shr:8 row_mask:0xf bank_mask:0xf
	v_mul_f32_dpp v14, v14, v14 row_shr:8 row_mask:0xf bank_mask:0xf
	v_mul_f32_dpp v15, v15, v15 row_shr:8 row_mask:0xf bank_mask:0xf
	v_fmac_f32_dpp v24, v24, v8 row_bcast:15 row_mask:0xa bank_mask:0xf
	v_fmac_f32_dpp v25, v25, v9 row_bcast:15 row_mask:0xa bank_mask:0xf
	v_fmac_f32_dpp v26, v26, v10 row_bcast:15 row_mask:0xa bank_mask:0xf
	v_fmac_f32_dpp v27, v27, v11 row_bcast:15 row_mask:0xa bank_mask:0xf
	v_fmac_f32_dpp v28, v28, v12 row_bcast:15 row_mask:0xa bank_mask:0xf
	v_fmac_f32_dpp v29, v29, v13 row_bcast:15 row_mask:0xa bank_mask:0xf
	v_fmac_f32_dpp v30, v30, v14 row_bcast:15 row_mask:0xa bank_mask:0xf
	v_fmac_f32_dpp v31, v31, v15 row_bcast:15 row_mask:0xa bank_mask:0xf
	v_mul_f32_dpp v8, v8, v8 row_bcast:15 row_mask:0xa bank_mask:0xf
	v_mul_f32_dpp v9, v9, v9 row_bcast:15 row_mask:0xa bank_mask:0xf
	v_mul_f32_dpp v10, v10, v10 row_bcast:15 row_mask:0xa bank_mask:0xf
	v_mul_f32_dpp v11, v11, v11 row_bcast:15 row_mask:0xa bank_mask:0xf
	v_mul_f32_dpp v12, v12, v12 row_bcast:15 row_mask:0xa bank_mask:0xf
	v_mul_f32_dpp v13, v13, v13 row_bcast:15 row_mask:0xa bank_mask:0xf
	v_mul_f32_dpp v14, v14, v14 row_bcast:15 row_mask:0xa bank_mask:0xf
	v_mul_f32_dpp v15, v15, v15 row_bcast:15 row_mask:0xa bank_mask:0xf

	s_and_saveexec_b64 s[84:85], s[12:13]
	s_cbranch_execz .LBB0_938
	s_lshl_b32 s1, s78, 2
	s_add_i32 s1, vcc_lo, s1
	v_lshl_add_u32 v32, v64, 2, s1
	ds_write_b128 v32, v[0:3] offset:2048
	ds_write_b128 v32, v[16:19] offset:2176
	ds_write_b128 v32, v[4:7] offset:2080
	ds_write_b128 v32, v[20:23] offset:2208
	ds_write_b128 v32, v[8:11] offset:2112
	ds_write_b128 v32, v[24:27] offset:2240
	ds_write_b128 v32, v[12:15] offset:2144
	ds_write_b128 v32, v[28:31] offset:2272
